# FFN-up: workgroups with c>=128 (one unit fewer) start ~12us late to de-synchronise store/load bursts
# baseline (speedup 1.0000x reference)
; #define PG8_STAGE(bufoff, gbase, voff) do { _Pragma("unroll") for (int _i = 0; _i < 2; ++_i) { unsigned _vo = (voff)[_i]; asm volatile("" : "+v"(_vo));   \
;         __builtin_amdgcn_global_load_lds((const unsigned*)((const char*)(gbase) + _vo), (LAS unsigned*)(lds + (bufoff) + ldsw + _i * 8192), 16, 0, 0); } } while (0)
; #define PG8_BAR __builtin_amdgcn_s_barrier()
; __device__ __forceinline__ void gemm_phase(LAS unsigned char* lds, const Call& C, const int tid, const Args& args) {
;     const int wid = __builtin_amdgcn_readfirstlane(tid >> 6), lane = tid & 63, wr = wid >> 2, wc = wid & 3, fr = lane & 15, fq = lane >> 4;
;     unsigned voffA[2], voffB[2];
; #pragma unroll
;     for (int i = 0; i < 2; ++i) { int R, Cc; stage_rc(tid * 16 + i * 8192, R, Cc); const int Rb = (R & ~31) + perm32(R & 31);
;         voffA[i] = (unsigned)(R * C.lda + Cc) * 2u; voffB[i] = (unsigned)(Rb * C.ldb + Cc) * 2u; }
;     const size_t kstep = (size_t)(BK * 2);
;     const size_t hstepA = (size_t)HALF * C.lda * 2, hstepB = (size_t)HALF * C.ldb * 2;
;     const unsigned ldsw = (unsigned)wid * 1024u;
;     const int aoff = lds_byte(wr * 64 + fr, fq * 8), boff = lds_byte(wc * 32 + fr, fq * 8);
;     ...
;     Unit cur, nxt; int ui = 0;
;     next_unit(C, 0, cur.pm, cur.pn, cur.kp0, cur.np, cur.slice);
;     if (cur.pm < 0) return;
;     f32x4 acc[2][2][4][2];
; #pragma unroll
;     for (int a = 0; a < 2; ++a)
; #pragma unroll
;         for (int b = 0; b < 2; ++b)
; #pragma unroll
;             for (int m = 0; m < 4; ++m)
; #pragma unroll
;                 for (int n = 0; n < 2; ++n) acc[a][b][m][n] = (f32x4){0.f, 0.f, 0.f, 0.f};
;     bf16x8 At[4][2], B0[2][2], B1[2][2];
;     const char* cA = PG8_APTR(cur); const char* cB = PG8_BPTR(cur);
;     PG8_STAGE(PG8_SB(0, 0), cB, voffB); PG8_STAGE(PG8_SB(0, 1), cB + hstepB, voffB); PG8_STAGE(PG8_SA(0, 0), cA, voffA); PG8_STAGE(PG8_SA(0, 1), cA + hstepA, voffA);
;     if (wr == 1) PG8_BAR;
.LBB0_261:
	v_readlane_b32 s24, v254, 19
	v_readlane_b32 s48, v254, 17
	s_cmp_lt_i32 s90, 0
	v_lshlrev_b32_e32 v85, 4, v204
	v_readlane_b32 s4, v254, 11
	v_readlane_b32 s25, v254, 20
	v_readlane_b32 s42, v254, 31
	v_readlane_b32 s44, v254, 39
	v_readlane_b32 s49, v254, 18
	s_cbranch_scc1 .LBB0_502
	s_cmp_lg_u32 s4, 9
	s_cbranch_scc1 .Lds_skip
	s_cmp_lt_u32 s21, 128
	s_cbranch_scc1 .Lds_skip
	s_sleep 127
	s_sleep 127
	s_sleep 127
.Lds_skip:
	v_ashrrev_i32_e32 v1, 31, v85
	v_lshrrev_b32_e32 v1, 22, v1
	v_add_u32_e32 v1, v85, v1
	v_and_b32_e32 v1, 0xfffffc00, v1
	v_sub_u32_e32 v1, v85, v1
	v_ashrrev_i32_e32 v0, 31, v204
	v_lshrrev_b32_e32 v2, 4, v1
	v_lshrrev_b32_e32 v0, 26, v0
	v_bitop3_b32 v2, v2, v1, 32 bitop3:0x6c
	v_ashrrev_i32_e32 v1, 31, v1
	v_add_u32_e32 v0, v204, v0
	v_lshrrev_b32_e32 v1, 26, v1
	v_ashrrev_i32_e32 v0, 6, v0
	v_add_u32_e32 v1, v2, v1
	v_lshlrev_b32_e32 v3, 3, v0
	v_ashrrev_i32_e32 v4, 6, v1
	v_and_b32_e32 v1, 0xc0, v1
	v_and_b32_e32 v3, -16, v3
	v_lshlrev_b32_e32 v0, 5, v0
	v_sub_u32_e32 v1, v2, v1
	v_add_u32_e32 v3, v4, v3
	v_and_b32_e32 v0, 32, v0
	v_ashrrev_i16_sdwa v1, v226, sext(v1) dst_sel:DWORD dst_unused:UNUSED_PAD src0_sel:DWORD src1_sel:BYTE_0
	v_add_u32_sdwa v0, v0, sext(v1) dst_sel:DWORD dst_unused:UNUSED_PAD src0_sel:DWORD src1_sel:WORD_0
	v_lshlrev_b32_e32 v1, 1, v3
	v_lshrrev_b32_e32 v2, 2, v3
	v_and_b32_e32 v4, 3, v4
	s_mov_b32 s4, 0x7fffffe0
	v_and_b32_e32 v1, 24, v1
	v_and_b32_e32 v2, 4, v2
	v_and_or_b32 v4, v3, s4, v4
	v_or3_b32 v1, v4, v2, v1
	v_mul_lo_u32 v2, s52, v3
	v_mul_lo_u32 v1, s52, v1
	v_add_lshl_u32 v205, v2, v0, 1
	v_add_lshl_u32 v242, v1, v0, 1
	v_add_u32_e32 v0, 0x2000, v85
	v_ashrrev_i32_e32 v1, 31, v0
	v_lshrrev_b32_e32 v1, 22, v1
	v_add_u32_e32 v1, v0, v1
	v_ashrrev_i32_e32 v1, 10, v1
	v_mul_i32_i24_e32 v2, 0x400, v1
	v_sub_u32_e32 v0, v0, v2
	v_lshrrev_b32_e32 v2, 4, v0
	v_bitop3_b32 v0, v2, v0, 32 bitop3:0x6c
	v_ashrrev_i32_e32 v3, 31, v0
	v_writelane_b32 v254, s51, 52
	v_lshrrev_b32_e32 v3, 26, v3
	v_writelane_b32 v254, s88, 53
	v_lshlrev_b32_e32 v2, 3, v1
	v_add_u32_e32 v3, v0, v3
	v_writelane_b32 v254, s89, 54
	v_and_b32_e32 v2, -16, v2
	v_ashrrev_i32_e32 v4, 6, v3
	v_writelane_b32 v254, s90, 55
	v_add_u32_e32 v2, v4, v2
	v_and_b32_e32 v4, 3, v4
	v_writelane_b32 v254, s91, 56
	s_ashr_i32 s12, s5, 6
	v_and_or_b32 v4, v2, s4, v4
	s_lshl_b32 s22, s52, 8
	s_mov_b32 s53, s29
	s_lshl_b32 s4, s90, 1
	s_ashr_i32 s13, s5, 8
	s_lshl_b64 s[74:75], s[52:53], 8
	s_lshl_b32 s23, s12, 10
	s_mul_hi_u32 s8, s4, s22
	s_mul_i32 s4, s4, s22
	v_readlane_b32 s34, v254, 25
	v_readlane_b32 s35, v254, 26
	s_add_u32 s4, s34, s4
	s_addc_u32 s14, s35, s8
	s_ashr_i32 s8, s78, 31
	s_lshl_b64 s[76:77], s[52:53], 9
	v_and_b32_e32 v3, 0xc0, v3
	s_mul_i32 s8, s76, s8
	s_mul_hi_u32 s9, s76, s78
	v_lshlrev_b32_e32 v1, 5, v1
	v_sub_u32_e32 v0, v0, v3
	s_add_i32 s8, s9, s8
	s_lshr_b32 s9, s52, 23
	v_and_b32_e32 v1, 32, v1
	v_ashrrev_i16_sdwa v0, v226, sext(v0) dst_sel:DWORD dst_unused:UNUSED_PAD src0_sel:DWORD src1_sel:BYTE_0
	s_mul_i32 s9, s9, s78
	v_add_u32_sdwa v0, v1, sext(v0) dst_sel:DWORD dst_unused:UNUSED_PAD src0_sel:DWORD src1_sel:WORD_0
	v_lshlrev_b32_e32 v1, 1, v2
	v_lshrrev_b32_e32 v3, 2, v2
	s_add_i32 s8, s8, s9
	s_mul_i32 s9, s76, s78
	v_and_b32_e32 v1, 24, v1
	v_and_b32_e32 v3, 4, v3
	s_add_u32 s9, s24, s9
	v_or3_b32 v1, v4, v3, v1
	s_addc_u32 s17, s25, s8
	v_mul_lo_u32 v2, s52, v2
	v_mul_lo_u32 v1, s52, v1
	s_add_u32 s8, s9, s0
	v_add_lshl_u32 v243, v2, v0, 1
	v_add_lshl_u32 v244, v1, v0, 1
	s_addc_u32 s9, s17, s1
	s_add_i32 s20, s23, 0
	v_mov_b32_e32 v0, v242
	s_add_i32 m0, s20, 0x10000
	s_nop 0
	global_load_lds_dwordx4 v0, s[8:9]
	v_mov_b32_e32 v0, v244
	s_add_i32 m0, s20, 0x12000
	s_add_u32 s34, s8, s74
	global_load_lds_dwordx4 v0, s[8:9]
	v_mov_b32_e32 v0, v242
	s_addc_u32 s35, s9, s75
	s_add_i32 m0, s20, 0x14000
	s_nop 0
	global_load_lds_dwordx4 v0, s[34:35]
	v_mov_b32_e32 v0, v244
	s_add_i32 m0, s20, 0x16000
	s_add_u32 s0, s4, s0
	global_load_lds_dwordx4 v0, s[34:35]
	v_mov_b32_e32 v0, v205
	s_addc_u32 s1, s14, s1
	s_mov_b32 m0, s20
	s_add_i32 s72, s20, 0x2000
	global_load_lds_dwordx4 v0, s[0:1]
	v_mov_b32_e32 v0, v243
	s_mov_b32 m0, s72
	s_add_u32 s24, s0, s22
	global_load_lds_dwordx4 v0, s[0:1]
	s_addc_u32 s25, s1, 0
	s_add_i32 s73, s20, 0x4000
	v_mov_b32_e32 v0, v205
	s_mov_b32 m0, s73
	s_add_i32 s4, s20, 0x6000
	global_load_lds_dwordx4 v0, s[24:25]
	v_mov_b32_e32 v0, v243
	s_mov_b32 m0, s4
	s_cmp_eq_u32 s13, 1
	global_load_lds_dwordx4 v0, s[24:25]
	s_cselect_b64 s[24:25], -1, 0
	v_writelane_b32 v254, s24, 57
	s_cmp_lg_u32 s13, 1
	s_nop 0
	v_writelane_b32 v254, s25, 58
	s_cbranch_scc1 .LBB0_264
	s_barrier
